# P2: mixer-B units moved off the 64 compression workgroups (critical path) onto the other 192
# baseline (speedup 1.0000x reference)
; __global__ void __launch_bounds__(512, 2) fwd_mega(Params P) {
;     ...
;         if (G > 64) {
;             if (bx < 64) { for (int j = 0; j < 4; ++j) { const int u = bx * 4 + j, qb = u & 63, bh = u >> 6; b_unit(Z, MIX, P.in[12], lds, bh >> 1, bh & 1, qb, gt, wave0); } }
;             else { for (int u = 256 + (bx - 64); u < 2048; u += G - 64) { const int qb = u & 63, bh = u >> 6; b_unit(Z, MIX, P.in[12], lds, bh >> 1, bh & 1, qb, gt, wave0); } }
;         } else { for (int u = bx; u < 2048; u += G) { const int qb = u & 63, bh = u >> 6; b_unit(Z, MIX, P.in[12], lds, bh >> 1, bh & 1, qb, gt, wave0); } }
.LBB0_492:
	s_and_b64 vcc, exec, s[84:85]
	s_cbranch_vccz .Lb_skip_units
	s_cmpk_gt_u32 s89, 0x73f
	s_mov_b32 s3, 0
	s_cbranch_scc1 .LBB0_550
	s_mov_b32 s69, 0
	s_mov_b32 s68, s69
	s_mov_b32 s70, s69
	s_mov_b32 s71, s69
	s_mov_b32 s72, s69
	s_mov_b32 s73, s69
	s_mov_b32 s74, s69
	s_mov_b32 s75, s69
	s_mov_b32 s76, s69
	s_mov_b32 s77, s69
	s_mov_b32 s78, s69
	s_mov_b32 s79, s69
	s_mov_b32 s80, s69
	s_mov_b32 s81, s69
	s_mov_b32 s82, s69
	s_mov_b32 s83, s69
	v_mov_b64_e32 v[0:1], s[68:69]
	s_add_i32 s2, s89, -64
	s_sub_i32 s33, s94, 64
	s_movk_i32 s84, 0x1600
	v_mov_b64_e32 v[160:161], s[86:87]
	v_mov_b32_e32 v163, 0
	v_mov_b64_e32 v[2:3], s[70:71]
	v_mov_b64_e32 v[4:5], s[72:73]
	v_mov_b64_e32 v[6:7], s[74:75]
	v_mov_b64_e32 v[8:9], s[76:77]
	v_mov_b64_e32 v[10:11], s[78:79]
	v_mov_b64_e32 v[12:13], s[80:81]
	v_mov_b64_e32 v[14:15], s[82:83]
	s_mov_b32 s76, 0xff800000
	s_mov_b32 s77, 0x40c00000
	v_mov_b32_e32 v170, 0x1600
	v_mov_b32_e32 v171, 0xff800000
	s_mov_b32 s82, 0

; __global__ void __launch_bounds__(512, 2) fwd_mega(Params P) {
;     ...
;         if (G > 64) {
;             if (bx < 64) { for (int j = 0; j < 4; ++j) { const int u = bx * 4 + j, qb = u & 63, bh = u >> 6; b_unit(Z, MIX, P.in[12], lds, bh >> 1, bh & 1, qb, gt, wave0); } }
;             else { for (int u = 256 + (bx - 64); u < 2048; u += G - 64) { const int qb = u & 63, bh = u >> 6; b_unit(Z, MIX, P.in[12], lds, bh >> 1, bh & 1, qb, gt, wave0); } }
;         } else { for (int u = bx; u < 2048; u += G) { const int qb = u & 63, bh = u >> 6; b_unit(Z, MIX, P.in[12], lds, bh >> 1, bh & 1, qb, gt, wave0); } }
;         __syncthreads();
.LBB0_605:
	v_readlane_b32 s81, v254, 11
	s_branch .LBB0_606
.Lb_skip_units:
	s_mov_b32 s3, 0
